# v77 + phase 0 w_in transpose: one item = 64 consecutive k of an output row (128 contiguous bytes per lane, all loads in flight) instead of 8
# speedup vs baseline: 1.0176x; 1.0031x over previous
.LBB0_29:
	s_or_b64 exec, exec, s[14:15]
	s_lshl_b32 s4, s2, 9
	v_writelane_b32 v250, s4, 1
	v_add_u32_e32 v4, s4, v14
	s_mov_b32 s4, 0x14000
	s_lshl_b32 s16, s33, 9
	v_cmp_gt_i32_e32 vcc, s4, v4
	s_and_saveexec_b64 s[6:7], vcc
	s_cbranch_execz .LBB0_48
	s_load_dwordx4 s[8:11], s[0:1], 0x28
	s_add_u32 s12, s38, 0x4920000
	v_lshlrev_b32_e32 v0, 4, v14
	s_addc_u32 s13, s39, 0
	v_lshl_add_u32 v5, s2, 13, v0
	s_lshl_b32 s4, s16, 4
	s_mov_b64 s[14:15], 0
	s_mov_b32 s5, 0x66666667
	s_movk_i32 s17, 0xff
	s_movk_i32 s26, 0x1ff
	s_movk_i32 s27, 0x3ff
	s_movk_i32 s28, 0xbff
	s_movk_i32 s29, 0x600
	s_movk_i32 s30, 0x3a0
	s_movk_i32 s31, 0x1a0
	v_mov_b32_e32 v7, 0
	s_mov_b32 s34, 0x13fff
	s_mov_b64 s[44:45], 0x4e80
	v_mov_b32_e32 v12, v4
	s_branch .LBB0_32
.LBB0_31:
	s_or_b64 exec, exec, s[18:19]
	v_ashrrev_i32_e32 v9, 31, v8
	v_lshlrev_b64 v[8:9], 11, v[8:9]
	v_add_u32_e32 v12, s16, v12
	v_lshl_add_u64 v[8:9], s[12:13], 0, v[8:9]
	v_cmp_lt_i32_e32 vcc, s34, v12
	v_lshl_add_u64 v[8:9], v[10:11], 1, v[8:9]
	s_or_b64 s[14:15], vcc, s[14:15]
	v_add_u32_e32 v5, s4, v5
	global_store_dwordx4 v[8:9], v[0:3], off
	global_store_dwordx4 v[8:9], v[170:173], off offset:16
	global_store_dwordx4 v[8:9], v[174:177], off offset:32
	global_store_dwordx4 v[8:9], v[178:181], off offset:48
	global_store_dwordx4 v[8:9], v[182:185], off offset:64
	global_store_dwordx4 v[8:9], v[186:189], off offset:80
	global_store_dwordx4 v[8:9], v[190:193], off offset:96
	global_store_dwordx4 v[8:9], v[194:197], off offset:112
	s_andn2_b64 exec, exec, s[14:15]
	s_cbranch_execz .LBB0_48

.LBB0_46:
	s_or_b64 exec, exec, s[18:19]
	v_lshlrev_b32_e32 v10, 6, v0
	v_cmp_gt_i32_e32 vcc, 0, v6
	v_ashrrev_i32_e32 v11, 31, v10
	s_and_saveexec_b64 s[18:19], vcc
	s_xor_b64 s[18:19], exec, s[18:19]
	s_or_saveexec_b64 s[18:19], s[18:19]
	v_mov_b32_e32 v0, 0
	v_mov_b32_e32 v1, 0
	v_mov_b32_e32 v2, 0
	v_mov_b32_e32 v3, 0
	v_mov_b32_e32 v170, 0
	v_mov_b32_e32 v171, 0
	v_mov_b32_e32 v172, 0
	v_mov_b32_e32 v173, 0
	v_mov_b32_e32 v174, 0
	v_mov_b32_e32 v175, 0
	v_mov_b32_e32 v176, 0
	v_mov_b32_e32 v177, 0
	v_mov_b32_e32 v178, 0
	v_mov_b32_e32 v179, 0
	v_mov_b32_e32 v180, 0
	v_mov_b32_e32 v181, 0
	v_mov_b32_e32 v182, 0
	v_mov_b32_e32 v183, 0
	v_mov_b32_e32 v184, 0
	v_mov_b32_e32 v185, 0
	v_mov_b32_e32 v186, 0
	v_mov_b32_e32 v187, 0
	v_mov_b32_e32 v188, 0
	v_mov_b32_e32 v189, 0
	v_mov_b32_e32 v190, 0
	v_mov_b32_e32 v191, 0
	v_mov_b32_e32 v192, 0
	v_mov_b32_e32 v193, 0
	v_mov_b32_e32 v194, 0
	v_mov_b32_e32 v195, 0
	v_mov_b32_e32 v196, 0
	v_mov_b32_e32 v197, 0
	s_xor_b64 exec, exec, s[18:19]
	s_cbranch_execz .LBB0_31
	s_waitcnt lgkmcnt(0)
	v_lshl_add_u64 v[20:21], v[6:7], 2, s[10:11]
	v_mul_u32_u24_e32 v22, 0x4e80, v10
	v_mov_b32_e32 v23, 0
	v_lshl_add_u64 v[20:21], v[22:23], 0, v[20:21]
	v_lshl_add_u64 v[24:25], v[10:11], 2, s[8:9]
	global_load_dword v42, v[20:21], off
	v_lshl_add_u64 v[20:21], v[20:21], 0, s[44:45]
	global_load_dword v43, v[20:21], off
	v_lshl_add_u64 v[20:21], v[20:21], 0, s[44:45]
	global_load_dword v44, v[20:21], off
	v_lshl_add_u64 v[20:21], v[20:21], 0, s[44:45]
	global_load_dword v45, v[20:21], off
	v_lshl_add_u64 v[20:21], v[20:21], 0, s[44:45]
	global_load_dword v46, v[20:21], off
	v_lshl_add_u64 v[20:21], v[20:21], 0, s[44:45]
	global_load_dword v47, v[20:21], off
	v_lshl_add_u64 v[20:21], v[20:21], 0, s[44:45]
	global_load_dword v48, v[20:21], off
	v_lshl_add_u64 v[20:21], v[20:21], 0, s[44:45]
	global_load_dword v49, v[20:21], off
	v_lshl_add_u64 v[20:21], v[20:21], 0, s[44:45]
	global_load_dword v50, v[20:21], off
	v_lshl_add_u64 v[20:21], v[20:21], 0, s[44:45]
	global_load_dword v51, v[20:21], off
	v_lshl_add_u64 v[20:21], v[20:21], 0, s[44:45]
	global_load_dword v52, v[20:21], off
	v_lshl_add_u64 v[20:21], v[20:21], 0, s[44:45]
	global_load_dword v53, v[20:21], off
	v_lshl_add_u64 v[20:21], v[20:21], 0, s[44:45]
	global_load_dword v54, v[20:21], off
	v_lshl_add_u64 v[20:21], v[20:21], 0, s[44:45]
	global_load_dword v55, v[20:21], off
	v_lshl_add_u64 v[20:21], v[20:21], 0, s[44:45]
	global_load_dword v56, v[20:21], off
	v_lshl_add_u64 v[20:21], v[20:21], 0, s[44:45]
	global_load_dword v57, v[20:21], off
	v_lshl_add_u64 v[20:21], v[20:21], 0, s[44:45]
	global_load_dword v58, v[20:21], off
	v_lshl_add_u64 v[20:21], v[20:21], 0, s[44:45]
	global_load_dword v59, v[20:21], off
	v_lshl_add_u64 v[20:21], v[20:21], 0, s[44:45]
	global_load_dword v60, v[20:21], off
	v_lshl_add_u64 v[20:21], v[20:21], 0, s[44:45]
	global_load_dword v61, v[20:21], off
	v_lshl_add_u64 v[20:21], v[20:21], 0, s[44:45]
	global_load_dword v62, v[20:21], off
	v_lshl_add_u64 v[20:21], v[20:21], 0, s[44:45]
	global_load_dword v63, v[20:21], off
	v_lshl_add_u64 v[20:21], v[20:21], 0, s[44:45]
	global_load_dword v64, v[20:21], off
	v_lshl_add_u64 v[20:21], v[20:21], 0, s[44:45]
	global_load_dword v65, v[20:21], off
	v_lshl_add_u64 v[20:21], v[20:21], 0, s[44:45]
	global_load_dword v66, v[20:21], off
	v_lshl_add_u64 v[20:21], v[20:21], 0, s[44:45]
	global_load_dword v67, v[20:21], off
	v_lshl_add_u64 v[20:21], v[20:21], 0, s[44:45]
	global_load_dword v68, v[20:21], off
	v_lshl_add_u64 v[20:21], v[20:21], 0, s[44:45]
	global_load_dword v69, v[20:21], off
	v_lshl_add_u64 v[20:21], v[20:21], 0, s[44:45]
	global_load_dword v70, v[20:21], off
	v_lshl_add_u64 v[20:21], v[20:21], 0, s[44:45]
	global_load_dword v71, v[20:21], off
	v_lshl_add_u64 v[20:21], v[20:21], 0, s[44:45]
	global_load_dword v72, v[20:21], off
	v_lshl_add_u64 v[20:21], v[20:21], 0, s[44:45]
	global_load_dword v73, v[20:21], off
	v_lshl_add_u64 v[20:21], v[20:21], 0, s[44:45]
	global_load_dword v74, v[20:21], off
	v_lshl_add_u64 v[20:21], v[20:21], 0, s[44:45]
	global_load_dword v75, v[20:21], off
	v_lshl_add_u64 v[20:21], v[20:21], 0, s[44:45]
	global_load_dword v76, v[20:21], off
	v_lshl_add_u64 v[20:21], v[20:21], 0, s[44:45]
	global_load_dword v77, v[20:21], off
	v_lshl_add_u64 v[20:21], v[20:21], 0, s[44:45]
	global_load_dword v78, v[20:21], off
	v_lshl_add_u64 v[20:21], v[20:21], 0, s[44:45]
	global_load_dword v79, v[20:21], off
	v_lshl_add_u64 v[20:21], v[20:21], 0, s[44:45]
	global_load_dword v80, v[20:21], off
	v_lshl_add_u64 v[20:21], v[20:21], 0, s[44:45]
	global_load_dword v81, v[20:21], off
	v_lshl_add_u64 v[20:21], v[20:21], 0, s[44:45]
	global_load_dword v82, v[20:21], off
	v_lshl_add_u64 v[20:21], v[20:21], 0, s[44:45]
	global_load_dword v83, v[20:21], off
	v_lshl_add_u64 v[20:21], v[20:21], 0, s[44:45]
	global_load_dword v84, v[20:21], off
	v_lshl_add_u64 v[20:21], v[20:21], 0, s[44:45]
	global_load_dword v85, v[20:21], off
	v_lshl_add_u64 v[20:21], v[20:21], 0, s[44:45]
	global_load_dword v86, v[20:21], off
	v_lshl_add_u64 v[20:21], v[20:21], 0, s[44:45]
	global_load_dword v87, v[20:21], off
	v_lshl_add_u64 v[20:21], v[20:21], 0, s[44:45]
	global_load_dword v88, v[20:21], off
	v_lshl_add_u64 v[20:21], v[20:21], 0, s[44:45]
	global_load_dword v89, v[20:21], off
	v_lshl_add_u64 v[20:21], v[20:21], 0, s[44:45]
	global_load_dword v90, v[20:21], off
	v_lshl_add_u64 v[20:21], v[20:21], 0, s[44:45]
	global_load_dword v91, v[20:21], off
	v_lshl_add_u64 v[20:21], v[20:21], 0, s[44:45]
	global_load_dword v92, v[20:21], off
	v_lshl_add_u64 v[20:21], v[20:21], 0, s[44:45]
	global_load_dword v93, v[20:21], off
	v_lshl_add_u64 v[20:21], v[20:21], 0, s[44:45]
	global_load_dword v94, v[20:21], off
	v_lshl_add_u64 v[20:21], v[20:21], 0, s[44:45]
	global_load_dword v95, v[20:21], off
	v_lshl_add_u64 v[20:21], v[20:21], 0, s[44:45]
	global_load_dword v96, v[20:21], off
	v_lshl_add_u64 v[20:21], v[20:21], 0, s[44:45]
	global_load_dword v97, v[20:21], off
	v_lshl_add_u64 v[20:21], v[20:21], 0, s[44:45]
	global_load_dword v98, v[20:21], off
	v_lshl_add_u64 v[20:21], v[20:21], 0, s[44:45]
	global_load_dword v99, v[20:21], off
	v_lshl_add_u64 v[20:21], v[20:21], 0, s[44:45]
	global_load_dword v100, v[20:21], off
	v_lshl_add_u64 v[20:21], v[20:21], 0, s[44:45]
	global_load_dword v101, v[20:21], off
	v_lshl_add_u64 v[20:21], v[20:21], 0, s[44:45]
	global_load_dword v102, v[20:21], off
	v_lshl_add_u64 v[20:21], v[20:21], 0, s[44:45]
	global_load_dword v103, v[20:21], off
	v_lshl_add_u64 v[20:21], v[20:21], 0, s[44:45]
	global_load_dword v104, v[20:21], off
	v_lshl_add_u64 v[20:21], v[20:21], 0, s[44:45]
	global_load_dword v105, v[20:21], off
	global_load_dwordx4 v[106:109], v[24:25], off
	global_load_dwordx4 v[110:113], v[24:25], off offset:16
	global_load_dwordx4 v[114:117], v[24:25], off offset:32
	global_load_dwordx4 v[118:121], v[24:25], off offset:48
	global_load_dwordx4 v[122:125], v[24:25], off offset:64
	global_load_dwordx4 v[126:129], v[24:25], off offset:80
	global_load_dwordx4 v[130:133], v[24:25], off offset:96
	global_load_dwordx4 v[134:137], v[24:25], off offset:112
	global_load_dwordx4 v[138:141], v[24:25], off offset:128
	global_load_dwordx4 v[142:145], v[24:25], off offset:144
	global_load_dwordx4 v[146:149], v[24:25], off offset:160
	global_load_dwordx4 v[150:153], v[24:25], off offset:176
	global_load_dwordx4 v[154:157], v[24:25], off offset:192
	global_load_dwordx4 v[158:161], v[24:25], off offset:208
	global_load_dwordx4 v[162:165], v[24:25], off offset:224
	global_load_dwordx4 v[166:169], v[24:25], off offset:240
	s_waitcnt vmcnt(0)
	v_pk_mul_f32 v[42:43], v[42:43], v[106:107]
	v_pk_mul_f32 v[44:45], v[44:45], v[108:109]
	v_pk_mul_f32 v[46:47], v[46:47], v[110:111]
	v_pk_mul_f32 v[48:49], v[48:49], v[112:113]
	v_pk_mul_f32 v[50:51], v[50:51], v[114:115]
	v_pk_mul_f32 v[52:53], v[52:53], v[116:117]
	v_pk_mul_f32 v[54:55], v[54:55], v[118:119]
	v_pk_mul_f32 v[56:57], v[56:57], v[120:121]
	v_pk_mul_f32 v[58:59], v[58:59], v[122:123]
	v_pk_mul_f32 v[60:61], v[60:61], v[124:125]
	v_pk_mul_f32 v[62:63], v[62:63], v[126:127]
	v_pk_mul_f32 v[64:65], v[64:65], v[128:129]
	v_pk_mul_f32 v[66:67], v[66:67], v[130:131]
	v_pk_mul_f32 v[68:69], v[68:69], v[132:133]
	v_pk_mul_f32 v[70:71], v[70:71], v[134:135]
	v_pk_mul_f32 v[72:73], v[72:73], v[136:137]
	v_pk_mul_f32 v[74:75], v[74:75], v[138:139]
	v_pk_mul_f32 v[76:77], v[76:77], v[140:141]
	v_pk_mul_f32 v[78:79], v[78:79], v[142:143]
	v_pk_mul_f32 v[80:81], v[80:81], v[144:145]
	v_pk_mul_f32 v[82:83], v[82:83], v[146:147]
	v_pk_mul_f32 v[84:85], v[84:85], v[148:149]
	v_pk_mul_f32 v[86:87], v[86:87], v[150:151]
	v_pk_mul_f32 v[88:89], v[88:89], v[152:153]
	v_pk_mul_f32 v[90:91], v[90:91], v[154:155]
	v_pk_mul_f32 v[92:93], v[92:93], v[156:157]
	v_pk_mul_f32 v[94:95], v[94:95], v[158:159]
	v_pk_mul_f32 v[96:97], v[96:97], v[160:161]
	v_pk_mul_f32 v[98:99], v[98:99], v[162:163]
	v_pk_mul_f32 v[100:101], v[100:101], v[164:165]
	v_pk_mul_f32 v[102:103], v[102:103], v[166:167]
	v_pk_mul_f32 v[104:105], v[104:105], v[168:169]
	v_cvt_pk_bf16_f32 v0, v42, v43
	v_cvt_pk_bf16_f32 v1, v44, v45
	v_cvt_pk_bf16_f32 v2, v46, v47
	v_cvt_pk_bf16_f32 v3, v48, v49
	v_cvt_pk_bf16_f32 v170, v50, v51
	v_cvt_pk_bf16_f32 v171, v52, v53
	v_cvt_pk_bf16_f32 v172, v54, v55
	v_cvt_pk_bf16_f32 v173, v56, v57
	v_cvt_pk_bf16_f32 v174, v58, v59
	v_cvt_pk_bf16_f32 v175, v60, v61
	v_cvt_pk_bf16_f32 v176, v62, v63
	v_cvt_pk_bf16_f32 v177, v64, v65
	v_cvt_pk_bf16_f32 v178, v66, v67
	v_cvt_pk_bf16_f32 v179, v68, v69
	v_cvt_pk_bf16_f32 v180, v70, v71
	v_cvt_pk_bf16_f32 v181, v72, v73
	v_cvt_pk_bf16_f32 v182, v74, v75
	v_cvt_pk_bf16_f32 v183, v76, v77
	v_cvt_pk_bf16_f32 v184, v78, v79
	v_cvt_pk_bf16_f32 v185, v80, v81
	v_cvt_pk_bf16_f32 v186, v82, v83
	v_cvt_pk_bf16_f32 v187, v84, v85
	v_cvt_pk_bf16_f32 v188, v86, v87
	v_cvt_pk_bf16_f32 v189, v88, v89
	v_cvt_pk_bf16_f32 v190, v90, v91
	v_cvt_pk_bf16_f32 v191, v92, v93
	v_cvt_pk_bf16_f32 v192, v94, v95
	v_cvt_pk_bf16_f32 v193, v96, v97
	v_cvt_pk_bf16_f32 v194, v98, v99
	v_cvt_pk_bf16_f32 v195, v100, v101
	v_cvt_pk_bf16_f32 v196, v102, v103
	v_cvt_pk_bf16_f32 v197, v104, v105
	s_branch .LBB0_31
